# grid-barrier and exchange poll loops: s_sleep 1 between polls shortened to s_sleep 0 (34 sites); on attention zero-hoist stack
# speedup vs baseline: 1.0016x; 1.0016x over previous
.LBB0_62:
	flat_load_dword v26, v[2:3] offset:1024 sc1
	flat_load_dword v1, v[2:3] offset:1280 sc1
	flat_load_dword v12, v[2:3] offset:1536 sc1
	flat_load_dword v13, v[2:3] offset:1792 sc1
	flat_load_dword v14, v[2:3] offset:2048 sc1
	flat_load_dword v15, v[2:3] offset:2304 sc1
	flat_load_dword v16, v[2:3] offset:2560 sc1
	flat_load_dword v17, v[2:3] offset:2816 sc1
	flat_load_dword v18, v[2:3] offset:3072 sc1
	flat_load_dword v19, v[2:3] offset:3328 sc1
	flat_load_dword v20, v[2:3] offset:3584 sc1
	flat_load_dword v21, v[2:3] offset:3840 sc1
	flat_load_dword v22, v[4:5] sc1
	flat_load_dword v23, v[6:7] sc1
	flat_load_dword v24, v[8:9] sc1
	flat_load_dword v25, v[10:11] sc1
	s_or_b64 s[10:11], s[10:11], exec
	s_or_b64 s[8:9], s[8:9], exec
	s_waitcnt vmcnt(0) lgkmcnt(0)
	v_add_u32_e32 v27, v1, v26
	v_add_u32_e32 v27, v27, v12
	v_add_u32_e32 v27, v27, v13
	v_add_u32_e32 v27, v27, v14
	v_add_u32_e32 v27, v27, v15
	v_add_u32_e32 v27, v27, v16
	v_add_u32_e32 v27, v27, v17
	v_add_u32_e32 v27, v27, v18
	v_add_u32_e32 v27, v27, v19
	v_add_u32_e32 v27, v27, v20
	v_add_u32_e32 v27, v27, v21
	v_add_u32_e32 v27, v27, v22
	v_add_u32_e32 v27, v27, v23
	v_add_u32_e32 v27, v27, v24
	v_add_u32_e32 v27, v27, v25
	v_cmp_ne_u32_e32 vcc, s22, v27
	s_and_saveexec_b64 s[12:13], vcc
	s_cbranch_execz .LBB0_61
	s_and_b32 s16, s23, 0xff
	s_mov_b64 s[14:15], -1
	s_cmp_eq_u32 s16, 0
	s_mov_b64 s[18:19], -1
	s_mov_b64 s[16:17], -1
	s_sleep 0
	s_cbranch_scc1 .LBB0_65
	s_and_saveexec_b64 s[20:21], s[18:19]
	s_cbranch_execz .LBB0_60
	s_branch .LBB0_68

.LBB0_76:
	s_and_b32 s18, s25, 0xff
	s_mov_b64 s[16:17], -1
	s_cmp_lg_u32 s18, 0
	s_mov_b64 s[18:19], -1
	s_sleep 0
	s_cbranch_scc1 .LBB0_80
	v_mov_b64_e32 v[2:3], s[38:39]
	flat_load_dword v2, v[2:3] offset:512 sc1
	s_mov_b64 s[18:19], 0
	s_mov_b64 s[20:21], -1
	s_waitcnt vmcnt(0) lgkmcnt(0)
	v_cmp_eq_u32_e32 vcc, 0, v2
	s_and_saveexec_b64 s[22:23], vcc
	s_cmp_lt_u32 s25, 0x40001
	s_cselect_b64 s[18:19], -1, 0
	s_xor_b64 s[20:21], exec, -1
	s_and_b64 s[18:19], s[18:19], exec
	s_or_b64 exec, exec, s[22:23]

.LBB0_90:
	s_and_b32 s16, s25, 0xff
	s_cmp_lg_u32 s16, 0
	s_mov_b64 s[18:19], -1
	s_sleep 0
	s_cbranch_scc0 .LBB0_92
	s_mov_b64 s[20:21], -1
	s_and_saveexec_b64 s[22:23], s[18:19]
	s_cbranch_execz .LBB0_89
	s_branch .LBB0_95

.LBB0_224:
	s_waitcnt vmcnt(0)
	flat_load_dwordx2 v[134:135], v[132:133] sc1
	flat_load_dwordx2 v[136:137], v[132:133] offset:8 sc1
	s_mov_b64 s[28:29], -1
	s_waitcnt vmcnt(0) lgkmcnt(0)
	v_cmp_eq_u32_e32 vcc, s34, v135
	v_cmp_eq_u32_e64 s[8:9], s34, v137
	s_and_b64 s[8:9], vcc, s[8:9]
	s_nop 0
	v_cndmask_b32_e64 v135, 0, 1, s[8:9]
	v_cmp_ne_u32_e32 vcc, 0, v135
	s_mov_b64 s[8:9], -1
	s_cmp_eq_u64 vcc, exec
	s_cbranch_scc1 .LBB0_223
	s_memrealtime s[8:9]
	s_waitcnt lgkmcnt(0)
	s_sub_u32 s8, s8, s26
	s_subb_u32 s9, s9, s27
	v_cmp_lt_u64_e32 vcc, s[8:9], v[232:233]
	s_cbranch_vccz .LBB0_222
	s_mov_b64 s[28:29], 0
	s_sleep 0
	s_branch .LBB0_222

.LBB0_366:
	v_mov_b64_e32 v[12:13], s[80:81]
	flat_load_dword v2, v[12:13] offset:1024 sc1
	flat_load_dword v0, v[12:13] offset:1280 sc1
	flat_load_dword v3, v[12:13] offset:1536 sc1
	flat_load_dword v4, v[12:13] offset:1792 sc1
	flat_load_dword v5, v[12:13] offset:2048 sc1
	flat_load_dword v6, v[12:13] offset:2304 sc1
	flat_load_dword v7, v[12:13] offset:2560 sc1
	flat_load_dword v8, v[12:13] offset:2816 sc1
	flat_load_dword v9, v[12:13] offset:3072 sc1
	flat_load_dword v10, v[12:13] offset:3328 sc1
	flat_load_dword v11, v[12:13] offset:3584 sc1
	s_nop 0
	flat_load_dword v12, v[12:13] offset:3840 sc1
	v_mov_b64_e32 v[14:15], s[6:7]
	flat_load_dword v13, v[14:15] sc1
	v_mov_b64_e32 v[14:15], s[8:9]
	flat_load_dword v14, v[14:15] sc1
	v_mov_b64_e32 v[16:17], s[10:11]
	flat_load_dword v15, v[16:17] sc1
	v_mov_b64_e32 v[16:17], s[14:15]
	flat_load_dword v16, v[16:17] sc1
	s_or_b64 s[22:23], s[22:23], exec
	s_or_b64 s[20:21], s[20:21], exec
	s_waitcnt vmcnt(0) lgkmcnt(0)
	v_add_u32_e32 v17, v0, v2
	v_add_u32_e32 v17, v17, v3
	v_add_u32_e32 v17, v17, v4
	v_add_u32_e32 v17, v17, v5
	v_add_u32_e32 v17, v17, v6
	v_add_u32_e32 v17, v17, v7
	v_add_u32_e32 v17, v17, v8
	v_add_u32_e32 v17, v17, v9
	v_add_u32_e32 v17, v17, v10
	v_add_u32_e32 v17, v17, v11
	v_add_u32_e32 v17, v17, v12
	v_add_u32_e32 v17, v17, v13
	v_add_u32_e32 v17, v17, v14
	v_add_u32_e32 v17, v17, v15
	v_add_u32_e32 v17, v17, v16
	v_cmp_ne_u32_e32 vcc, s36, v17
	s_and_saveexec_b64 s[24:25], vcc
	s_cbranch_execz .LBB0_365
	s_and_b32 s28, s37, 0xff
	s_mov_b64 s[26:27], -1
	s_cmp_eq_u32 s28, 0
	s_mov_b64 s[30:31], -1
	s_mov_b64 s[28:29], -1
	s_sleep 0
	s_cbranch_scc1 .LBB0_369
	s_and_saveexec_b64 s[34:35], s[30:31]
	s_cbranch_execz .LBB0_364
	s_branch .LBB0_372

.LBB0_384:
	s_and_b32 s22, s29, 0xff
	s_mov_b64 s[20:21], -1
	s_cmp_lg_u32 s22, 0
	s_mov_b64 s[22:23], -1
	s_sleep 0
	s_cbranch_scc1 .LBB0_388
	v_mov_b64_e32 v[4:5], s[80:81]
	flat_load_dword v0, v[4:5] offset:512 sc1
	s_mov_b64 s[22:23], 0
	s_mov_b64 s[24:25], -1
	s_waitcnt vmcnt(0) lgkmcnt(0)
	v_cmp_eq_u32_e32 vcc, 0, v0
	s_and_saveexec_b64 s[26:27], vcc
	s_cmp_lt_u32 s29, 0x40001
	s_cselect_b64 s[22:23], -1, 0
	s_xor_b64 s[24:25], exec, -1
	s_and_b64 s[22:23], s[22:23], exec
	s_or_b64 exec, exec, s[26:27]

.LBB0_398:
	s_and_b32 s22, s29, 0xff
	s_mov_b64 s[20:21], -1
	s_cmp_lg_u32 s22, 0
	s_mov_b64 s[24:25], -1
	s_sleep 0
	s_cbranch_scc0 .LBB0_400
	s_and_saveexec_b64 s[26:27], s[24:25]
	s_cbranch_execz .LBB0_397
	s_branch .LBB0_403

.LBB0_734:
	v_mov_b64_e32 v[12:13], s[78:79]
	flat_load_dword v2, v[12:13] offset:1024 sc1
	flat_load_dword v0, v[12:13] offset:1280 sc1
	flat_load_dword v3, v[12:13] offset:1536 sc1
	flat_load_dword v4, v[12:13] offset:1792 sc1
	flat_load_dword v5, v[12:13] offset:2048 sc1
	flat_load_dword v6, v[12:13] offset:2304 sc1
	flat_load_dword v7, v[12:13] offset:2560 sc1
	flat_load_dword v8, v[12:13] offset:2816 sc1
	flat_load_dword v9, v[12:13] offset:3072 sc1
	flat_load_dword v10, v[12:13] offset:3328 sc1
	flat_load_dword v11, v[12:13] offset:3584 sc1
	s_nop 0
	flat_load_dword v12, v[12:13] offset:3840 sc1
	v_mov_b64_e32 v[14:15], s[4:5]
	flat_load_dword v13, v[14:15] sc1
	v_mov_b64_e32 v[14:15], s[6:7]
	flat_load_dword v14, v[14:15] sc1
	v_mov_b64_e32 v[16:17], s[8:9]
	flat_load_dword v15, v[16:17] sc1
	v_mov_b64_e32 v[16:17], s[10:11]
	flat_load_dword v16, v[16:17] sc1
	s_or_b64 s[20:21], s[20:21], exec
	s_or_b64 s[18:19], s[18:19], exec
	s_waitcnt vmcnt(0) lgkmcnt(0)
	v_add_u32_e32 v17, v0, v2
	v_add_u32_e32 v17, v17, v3
	v_add_u32_e32 v17, v17, v4
	v_add_u32_e32 v17, v17, v5
	v_add_u32_e32 v17, v17, v6
	v_add_u32_e32 v17, v17, v7
	v_add_u32_e32 v17, v17, v8
	v_add_u32_e32 v17, v17, v9
	v_add_u32_e32 v17, v17, v10
	v_add_u32_e32 v17, v17, v11
	v_add_u32_e32 v17, v17, v12
	v_add_u32_e32 v17, v17, v13
	v_add_u32_e32 v17, v17, v14
	v_add_u32_e32 v17, v17, v15
	v_add_u32_e32 v17, v17, v16
	v_cmp_ne_u32_e32 vcc, s34, v17
	s_and_saveexec_b64 s[22:23], vcc
	s_cbranch_execz .LBB0_733
	s_and_b32 s26, s35, 0xff
	s_mov_b64 s[24:25], -1
	s_cmp_eq_u32 s26, 0
	s_mov_b64 s[28:29], -1
	s_mov_b64 s[26:27], -1
	s_sleep 0
	s_cbranch_scc1 .LBB0_737
	s_and_saveexec_b64 s[30:31], s[28:29]
	s_cbranch_execz .LBB0_732
	s_branch .LBB0_740

.LBB0_748:
	s_and_b32 s20, s27, 0xff
	s_mov_b64 s[18:19], -1
	s_cmp_lg_u32 s20, 0
	s_mov_b64 s[20:21], -1
	s_sleep 0
	s_cbranch_scc1 .LBB0_752
	v_mov_b64_e32 v[4:5], s[78:79]
	flat_load_dword v0, v[4:5] offset:512 sc1
	s_mov_b64 s[20:21], 0
	s_mov_b64 s[22:23], -1
	s_waitcnt vmcnt(0) lgkmcnt(0)
	v_cmp_eq_u32_e32 vcc, 0, v0
	s_and_saveexec_b64 s[24:25], vcc
	s_cmp_lt_u32 s27, 0x40001
	s_cselect_b64 s[20:21], -1, 0
	s_xor_b64 s[22:23], exec, -1
	s_and_b64 s[20:21], s[20:21], exec
	s_or_b64 exec, exec, s[24:25]

.LBB0_762:
	s_and_b32 s20, s27, 0xff
	s_mov_b64 s[18:19], -1
	s_cmp_lg_u32 s20, 0
	s_mov_b64 s[22:23], -1
	s_sleep 0
	s_cbranch_scc0 .LBB0_764
	s_and_saveexec_b64 s[24:25], s[22:23]
	s_cbranch_execz .LBB0_761
	s_branch .LBB0_767

.LBB0_924:
	flat_load_dwordx2 v[196:197], v[212:213] sc1
	flat_load_dwordx2 v[198:199], v[212:213] offset:8 sc1
	flat_load_dwordx2 v[200:201], v[212:213] offset:16 sc1
	flat_load_dwordx2 v[208:209], v[212:213] offset:24 sc1
	flat_load_dwordx2 v[210:211], v[212:213] offset:32 sc1
	flat_load_dwordx2 v[214:215], v[212:213] offset:40 sc1
	flat_load_dwordx2 v[216:217], v[212:213] offset:48 sc1
	flat_load_dwordx2 v[218:219], v[212:213] offset:56 sc1
	s_mov_b64 s[18:19], -1
	s_waitcnt vmcnt(0) lgkmcnt(0)
	v_cmp_eq_u32_e32 vcc, s27, v197
	v_cmp_eq_u32_e64 s[6:7], s27, v199
	s_and_b64 s[6:7], vcc, s[6:7]
	v_cmp_eq_u32_e32 vcc, s27, v201
	s_and_b64 s[6:7], s[6:7], vcc
	v_cmp_eq_u32_e32 vcc, s27, v209
	s_and_b64 s[6:7], s[6:7], vcc
	v_cmp_eq_u32_e32 vcc, s27, v211
	s_and_b64 s[6:7], s[6:7], vcc
	v_cmp_eq_u32_e32 vcc, s27, v215
	s_and_b64 s[6:7], s[6:7], vcc
	v_cmp_eq_u32_e32 vcc, s27, v217
	s_and_b64 s[6:7], s[6:7], vcc
	v_cmp_eq_u32_e32 vcc, s27, v219
	s_and_b64 s[6:7], s[6:7], vcc
	v_cndmask_b32_e64 v0, 0, 1, s[6:7]
	v_cmp_ne_u32_e32 vcc, 0, v0
	s_mov_b64 s[6:7], -1
	s_cmp_eq_u64 vcc, exec
	s_cbranch_scc1 .LBB0_923
	s_memrealtime s[6:7]
	s_waitcnt lgkmcnt(0)
	s_sub_u32 s6, s6, s16
	s_subb_u32 s7, s7, s17
	v_cmp_lt_u64_e32 vcc, s[6:7], v[232:233]
	s_cbranch_vccz .LBB0_922
	s_mov_b64 s[18:19], 0
	s_sleep 0
	s_branch .LBB0_922

.LBB0_984:
	flat_load_dwordx2 v[146:147], v[208:209] sc1
	flat_load_dwordx2 v[148:149], v[208:209] offset:8 sc1
	flat_load_dwordx2 v[200:201], v[208:209] offset:16 sc1
	flat_load_dwordx2 v[210:211], v[208:209] offset:24 sc1
	flat_load_dwordx2 v[212:213], v[208:209] offset:32 sc1
	flat_load_dwordx2 v[214:215], v[208:209] offset:40 sc1
	flat_load_dwordx2 v[216:217], v[208:209] offset:48 sc1
	flat_load_dwordx2 v[218:219], v[208:209] offset:56 sc1
	v_mov_b32_e32 v202, v1
	v_mov_b32_e32 v204, v1
	v_mov_b32_e32 v206, v1
	v_mov_b32_e32 v222, v1
	v_mov_b32_e32 v228, v1
	v_mov_b32_e32 v230, v1
	v_mov_b32_e32 v232, v1
	v_mov_b32_e32 v234, v1
	s_waitcnt vmcnt(0) lgkmcnt(0)
	v_mov_b32_e32 v203, v147
	v_mov_b32_e32 v205, v149
	v_mov_b32_e32 v207, v201
	v_cmp_eq_u64_e32 vcc, s[50:51], v[202:203]
	v_cmp_eq_u64_e64 s[6:7], s[50:51], v[204:205]
	v_mov_b32_e32 v223, v211
	v_cmp_eq_u64_e64 s[8:9], s[50:51], v[206:207]
	s_and_b64 s[6:7], vcc, s[6:7]
	v_mov_b32_e32 v229, v213
	v_cmp_eq_u64_e64 s[10:11], s[50:51], v[222:223]
	s_and_b64 s[6:7], s[6:7], s[8:9]
	v_mov_b32_e32 v231, v215
	v_cmp_eq_u64_e64 s[14:15], s[50:51], v[228:229]
	s_and_b64 s[6:7], s[6:7], s[10:11]
	v_mov_b32_e32 v233, v217
	v_cmp_eq_u64_e64 s[16:17], s[50:51], v[230:231]
	s_and_b64 s[6:7], s[6:7], s[14:15]
	v_mov_b32_e32 v235, v219
	v_cmp_eq_u64_e64 s[18:19], s[50:51], v[232:233]
	s_and_b64 s[6:7], s[6:7], s[16:17]
	v_cmp_eq_u64_e64 s[20:21], s[50:51], v[234:235]
	s_and_b64 s[6:7], s[6:7], s[18:19]
	s_and_b64 s[6:7], s[6:7], s[20:21]
	v_cndmask_b32_e64 v0, 0, 1, s[6:7]
	v_cmp_ne_u32_e32 vcc, 0, v0
	s_mov_b64 s[6:7], -1
	s_cmp_eq_u64 vcc, exec
	s_mov_b64 s[8:9], -1
	s_cbranch_scc1 .LBB0_983
	s_memrealtime s[6:7]
	v_mov_b64_e32 v[202:203], 0x1e8481
	s_waitcnt lgkmcnt(0)
	s_sub_u32 s6, s6, s24
	s_subb_u32 s7, s7, s25
	v_cmp_lt_u64_e32 vcc, s[6:7], v[202:203]
	s_cbranch_vccz .LBB0_982
	s_mov_b64 s[8:9], 0
	s_sleep 0
	s_branch .LBB0_982

.LBB0_1134:
	v_mov_b64_e32 v[12:13], s[74:75]
	flat_load_dword v2, v[12:13] offset:1024 sc1
	flat_load_dword v0, v[12:13] offset:1280 sc1
	flat_load_dword v3, v[12:13] offset:1536 sc1
	flat_load_dword v4, v[12:13] offset:1792 sc1
	flat_load_dword v5, v[12:13] offset:2048 sc1
	flat_load_dword v6, v[12:13] offset:2304 sc1
	flat_load_dword v7, v[12:13] offset:2560 sc1
	flat_load_dword v8, v[12:13] offset:2816 sc1
	flat_load_dword v9, v[12:13] offset:3072 sc1
	flat_load_dword v10, v[12:13] offset:3328 sc1
	flat_load_dword v11, v[12:13] offset:3584 sc1
	s_nop 0
	flat_load_dword v12, v[12:13] offset:3840 sc1
	v_mov_b64_e32 v[14:15], s[4:5]
	flat_load_dword v13, v[14:15] sc1
	v_mov_b64_e32 v[14:15], s[6:7]
	flat_load_dword v14, v[14:15] sc1
	v_mov_b64_e32 v[16:17], s[8:9]
	flat_load_dword v15, v[16:17] sc1
	v_mov_b64_e32 v[16:17], s[10:11]
	flat_load_dword v16, v[16:17] sc1
	s_or_b64 s[20:21], s[20:21], exec
	s_or_b64 s[18:19], s[18:19], exec
	s_waitcnt vmcnt(0) lgkmcnt(0)
	v_add_u32_e32 v17, v0, v2
	v_add_u32_e32 v17, v17, v3
	v_add_u32_e32 v17, v17, v4
	v_add_u32_e32 v17, v17, v5
	v_add_u32_e32 v17, v17, v6
	v_add_u32_e32 v17, v17, v7
	v_add_u32_e32 v17, v17, v8
	v_add_u32_e32 v17, v17, v9
	v_add_u32_e32 v17, v17, v10
	v_add_u32_e32 v17, v17, v11
	v_add_u32_e32 v17, v17, v12
	v_add_u32_e32 v17, v17, v13
	v_add_u32_e32 v17, v17, v14
	v_add_u32_e32 v17, v17, v15
	v_add_u32_e32 v17, v17, v16
	v_cmp_ne_u32_e32 vcc, s34, v17
	s_and_saveexec_b64 s[22:23], vcc
	s_cbranch_execz .LBB0_1133
	s_and_b32 s26, s35, 0xff
	s_mov_b64 s[24:25], -1
	s_cmp_eq_u32 s26, 0
	s_mov_b64 s[28:29], -1
	s_mov_b64 s[26:27], -1
	s_sleep 0
	s_cbranch_scc1 .LBB0_1137
	s_and_saveexec_b64 s[30:31], s[28:29]
	s_cbranch_execz .LBB0_1132
	s_branch .LBB0_1140

.LBB0_1148:
	s_and_b32 s20, s27, 0xff
	s_mov_b64 s[18:19], -1
	s_cmp_lg_u32 s20, 0
	s_mov_b64 s[20:21], -1
	s_sleep 0
	s_cbranch_scc1 .LBB0_1152
	v_mov_b64_e32 v[4:5], s[74:75]
	flat_load_dword v0, v[4:5] offset:512 sc1
	s_mov_b64 s[20:21], 0
	s_mov_b64 s[22:23], -1
	s_waitcnt vmcnt(0) lgkmcnt(0)
	v_cmp_eq_u32_e32 vcc, 0, v0
	s_and_saveexec_b64 s[24:25], vcc
	s_cmp_lt_u32 s27, 0x40001
	s_cselect_b64 s[20:21], -1, 0
	s_xor_b64 s[22:23], exec, -1
	s_and_b64 s[20:21], s[20:21], exec
	s_or_b64 exec, exec, s[24:25]

.LBB0_1242:
	flat_load_dwordx2 v[34:35], v[136:137] sc1
	flat_load_dwordx2 v[36:37], v[136:137] offset:8 sc1
	flat_load_dwordx2 v[38:39], v[136:137] offset:16 sc1
	flat_load_dwordx2 v[40:41], v[136:137] offset:24 sc1
	flat_load_dwordx2 v[132:133], v[136:137] offset:32 sc1
	flat_load_dwordx2 v[134:135], v[136:137] offset:40 sc1
	flat_load_dwordx2 v[146:147], v[136:137] offset:48 sc1
	flat_load_dwordx2 v[148:149], v[136:137] offset:56 sc1
	s_waitcnt vmcnt(0) lgkmcnt(0)
	v_cmp_eq_u32_e32 vcc, s30, v35
	v_cmp_eq_u32_e64 s[8:9], s30, v37
	v_cmp_eq_u32_e64 s[10:11], s30, v39
	s_and_b64 s[8:9], vcc, s[8:9]
	v_cmp_eq_u32_e64 s[14:15], s30, v41
	s_and_b64 s[8:9], s[8:9], s[10:11]
	v_cmp_eq_u32_e64 s[16:17], s30, v133
	s_and_b64 s[8:9], s[8:9], s[14:15]
	v_cmp_eq_u32_e64 s[18:19], s30, v135
	s_and_b64 s[8:9], s[8:9], s[16:17]
	v_cmp_eq_u32_e64 s[20:21], s30, v147
	s_and_b64 s[8:9], s[8:9], s[18:19]
	v_cmp_eq_u32_e64 s[22:23], s30, v149
	s_and_b64 s[8:9], s[8:9], s[20:21]
	s_and_b64 s[8:9], s[8:9], s[22:23]
	v_cndmask_b32_e64 v0, 0, 1, s[8:9]
	v_cmp_ne_u32_e32 vcc, 0, v0
	s_mov_b64 s[8:9], -1
	s_cmp_eq_u64 vcc, exec
	s_mov_b64 s[10:11], -1
	s_cbranch_scc1 .LBB0_1241
	s_memrealtime s[8:9]
	s_waitcnt lgkmcnt(0)
	s_sub_u32 s8, s8, s28
	s_subb_u32 s9, s9, s29
	v_cmp_lt_u64_e32 vcc, s[8:9], v[232:233]
	s_cbranch_vccz .LBB0_1240
	s_mov_b64 s[10:11], 0
	s_sleep 0
	s_branch .LBB0_1240
